# SSD: z/x gate loads interleaved through the staging code instead of issued as a burst
# speedup vs baseline: 1.0018x; 1.0018x over previous
; #define LAS __attribute__((address_space(3)))
; __device__ __forceinline__ float fexp(float x) { return __builtin_amdgcn_exp2f(x * 1.4426950408889634f); }
; __device__ __forceinline__ void ssd_item(const Params& P, LAS unsigned char* lds, int item, int tid, int wave, int lane) {
;     ...
;         for (int k = 0; k < 8; ++k) { const int br = brow0 + 16 * k;
;             u32x4 v = pbc[k]; if (br >= nvalid) v = (u32x4){0u, 0u, 0u, 0u};
;             *(LAS u32x4*)(lds + (bsel ? S_CC : S_BC) + br * LP + boct * 16) = v; }
;         {
;             const float aend = ACS[127];
; #pragma unroll
;             for (int q = 0; q < 2; ++q) { const int s = xrow0 + 64 * q; const bool sv = s < nvalid;
;                 const float dtv = DTV[s], dd = fexp(aend - ACS[s]);
;     ...
;             const int zb = __builtin_amdgcn_readfirstlane((int)(((unsigned)rowbase + p0 + wave * 16) * LDP * 2u));
; #pragma unroll
;             for (int i = 0; i < 4; ++i) { zc[i] = __builtin_bit_cast(u32x2, __builtin_amdgcn_raw_buffer_load_b64(prs, zvoff, zb + i * (LDP * 2), 2));
;                                           xc[i] = __builtin_bit_cast(u32x2, __builtin_amdgcn_raw_buffer_load_b64(prs, xvoff, zb + i * (LDP * 2), 2)); }
.LBB0_318:
	s_waitcnt vmcnt(4)
	s_lshl_b32 s98, s17, 7
	s_add_i32 s98, s98, s16
	s_mul_i32 s98, s98, 0x2c20
	s_add_i32 s99, s98, 0x2c20
	s_add_i32 s100, s98, 0x5840
	s_add_i32 s101, s98, 0x8460
	s_lshl_b32 s6, s17, 7
	s_sub_i32 s7, 0x1010, s6
	s_min_u32 s19, s7, 0x80
	v_cmp_gt_u32_e32 vcc, s19, v104
	s_lshl_b32 s7, s17, 9
	s_and_b32 s7, s7, 0x200
	v_cndmask_b32_e32 v19, 0, v51, vcc
	v_cndmask_b32_e32 v18, 0, v50, vcc
	v_cndmask_b32_e32 v17, 0, v49, vcc
	v_cndmask_b32_e32 v16, 0, v48, vcc
	v_cmp_gt_u32_e32 vcc, s19, v108
	ds_write_b128 v188, v[16:19]
	s_add_i32 s21, s7, 0
	v_cndmask_b32_e32 v19, 0, v55, vcc
	v_cndmask_b32_e32 v18, 0, v54, vcc
	v_cndmask_b32_e32 v17, 0, v53, vcc
	v_cndmask_b32_e32 v16, 0, v52, vcc
	v_cmp_gt_u32_e32 vcc, s19, v110
	ds_write_b128 v188, v[16:19] offset:4352
	s_add_i32 s21, s21, 0x26400
	v_cndmask_b32_e32 v19, 0, v59, vcc
	v_cndmask_b32_e32 v18, 0, v58, vcc
	v_cndmask_b32_e32 v17, 0, v57, vcc
	v_cndmask_b32_e32 v16, 0, v56, vcc
	buffer_load_dwordx2 v[160:161], v214, s[84:87], s98 offen nt
	v_cmp_gt_u32_e32 vcc, s19, v112
	ds_write_b128 v188, v[16:19] offset:8704
	v_lshlrev_b32_e32 v21, 16, v80
	v_cndmask_b32_e32 v19, 0, v63, vcc
	v_cndmask_b32_e32 v18, 0, v62, vcc
	v_cndmask_b32_e32 v17, 0, v61, vcc
	v_cndmask_b32_e32 v16, 0, v60, vcc
	v_cmp_gt_u32_e32 vcc, s19, v114
	ds_write_b128 v188, v[16:19] offset:13056
	s_add_i32 s20, s16, s6
	v_cndmask_b32_e32 v19, 0, v67, vcc
	v_cndmask_b32_e32 v18, 0, v66, vcc
	v_cndmask_b32_e32 v17, 0, v65, vcc
	v_cndmask_b32_e32 v16, 0, v64, vcc
	v_cmp_gt_u32_e32 vcc, s19, v116
	ds_write_b128 v188, v[16:19] offset:17408
	s_mul_i32 s6, s20, 0x2c20
	v_cndmask_b32_e32 v19, 0, v71, vcc
	v_cndmask_b32_e32 v18, 0, v70, vcc
	v_cndmask_b32_e32 v17, 0, v69, vcc
	v_cndmask_b32_e32 v16, 0, v68, vcc
	v_cmp_gt_u32_e32 vcc, s19, v118
	ds_write_b128 v188, v[16:19] offset:21760
	s_add_i32 s18, s6, 0x5840
	buffer_load_dwordx2 v[156:157], v214, s[84:87], s99 offen nt
	v_cndmask_b32_e32 v19, 0, v75, vcc
	v_cndmask_b32_e32 v18, 0, v74, vcc
	v_cndmask_b32_e32 v17, 0, v73, vcc
	v_cndmask_b32_e32 v16, 0, v72, vcc
	v_cmp_gt_u32_e32 vcc, s19, v168
	ds_write_b128 v188, v[16:19] offset:26112
	s_add_i32 s74, s6, 0x8460
	v_cndmask_b32_e32 v19, 0, v79, vcc
	v_cndmask_b32_e32 v18, 0, v78, vcc
	v_cndmask_b32_e32 v17, 0, v77, vcc
	v_cndmask_b32_e32 v16, 0, v76, vcc
	ds_write_b128 v188, v[16:19] offset:30464
	v_mov_b32_e32 v16, s21
	ds_read_b32 v20, v16 offset:508
	v_lshl_add_u32 v16, v122, 2, s21
	ds_read2st64_b32 v[16:17], v16 offset1:1
	v_add_u32_e32 v18, s7, v179
	ds_read2st64_b32 v[18:19], v18 offset1:1
	v_cmp_gt_u32_e32 vcc, s19, v122
	s_add_i32 s7, s6, 0x2c20
	s_waitcnt lgkmcnt(1)
	v_sub_f32_e32 v16, v20, v16
	v_mul_f32_e32 v16, 0x3fb8aa3b, v16
	v_exp_f32_e32 v16, v16
	buffer_load_dwordx2 v[150:151], v214, s[84:87], s100 offen nt
	v_cndmask_b32_e32 v21, 0, v21, vcc
	s_waitcnt lgkmcnt(0)
; #define LAS __attribute__((address_space(3)))
; __device__ __forceinline__ unsigned f2bf(float f) { return pk2(f, 0.f) & 0xffffu; }
; __device__ __forceinline__ float fexp(float x) { return __builtin_amdgcn_exp2f(x * 1.4426950408889634f); }
; __device__ __forceinline__ void ssd_item(const Params& P, LAS unsigned char* lds, int item, int tid, int wave, int lane) {
;     ...
;             for (int q = 0; q < 2; ++q) { const int s = xrow0 + 64 * q; const bool sv = s < nvalid;
;                 const float dtv = DTV[s], dd = fexp(aend - ACS[s]);
;                 const unsigned w4[4] = {pxv[q].x, pxv[q].y, pxv[q].z, pxv[q].w};
;                 const int sofs = (((s >> 3) ^ xoct) << 4) + (s & 7) * 2;
; #pragma unroll
;                 for (int j = 0; j < 8; ++j) { float x = (j & 1) ? bfhi(w4[j >> 1]) : bflo(w4[j >> 1]); x = sv ? x : 0.f; const int p = xoct * 8 + j;
;                     const float xd = x * dtv;
;                     *(LAS unsigned short*)(lds + S_XDTT + p * LP + sofs) = (unsigned short)f2bf(xd);
;                     *(LAS unsigned short*)(lds + S_XDDT + p * LP + sofs) = (unsigned short)f2bf(xd * dd); } }
;         }
;         __syncthreads();
	v_mul_f32_e32 v21, v21, v18
	v_cvt_pk_bf16_f32 v22, v21, s0
	v_mul_f32_e32 v21, v21, v16
	v_cvt_pk_bf16_f32 v21, v21, s0
	ds_write_b16 v190, v21
	v_and_b32_e32 v21, 0xffff0000, v80
	v_cndmask_b32_e32 v21, 0, v21, vcc
	v_mul_f32_e32 v21, v21, v18
	ds_write_b16 v189, v22
	v_cvt_pk_bf16_f32 v22, v21, s0
	v_mul_f32_e32 v21, v21, v16
	v_cvt_pk_bf16_f32 v21, v21, s0
	ds_write_b16 v190, v21 offset:272
	v_lshlrev_b32_e32 v21, 16, v81
	v_cndmask_b32_e32 v21, 0, v21, vcc
	v_mul_f32_e32 v21, v21, v18
	ds_write_b16 v189, v22 offset:272
	v_cvt_pk_bf16_f32 v22, v21, s0
	v_mul_f32_e32 v21, v21, v16
	v_cvt_pk_bf16_f32 v21, v21, s0
	ds_write_b16 v190, v21 offset:544
	v_and_b32_e32 v21, 0xffff0000, v81
	buffer_load_dwordx2 v[144:145], v214, s[84:87], s101 offen nt
	v_cndmask_b32_e32 v21, 0, v21, vcc
	v_mul_f32_e32 v21, v21, v18
	ds_write_b16 v189, v22 offset:544
	v_cvt_pk_bf16_f32 v22, v21, s0
	v_mul_f32_e32 v21, v21, v16
	v_cvt_pk_bf16_f32 v21, v21, s0
	ds_write_b16 v190, v21 offset:816
	v_lshlrev_b32_e32 v21, 16, v82
	v_cndmask_b32_e32 v21, 0, v21, vcc
	v_mul_f32_e32 v21, v21, v18
	ds_write_b16 v189, v22 offset:816
	v_cvt_pk_bf16_f32 v22, v21, s0
	v_mul_f32_e32 v21, v21, v16
	v_cvt_pk_bf16_f32 v21, v21, s0
	ds_write_b16 v190, v21 offset:1088
	v_and_b32_e32 v21, 0xffff0000, v82
	v_cndmask_b32_e32 v21, 0, v21, vcc
	v_mul_f32_e32 v21, v21, v18
	ds_write_b16 v189, v22 offset:1088
	v_cvt_pk_bf16_f32 v22, v21, s0
	v_mul_f32_e32 v21, v21, v16
	v_cvt_pk_bf16_f32 v21, v21, s0
	ds_write_b16 v190, v21 offset:1360
	v_lshlrev_b32_e32 v21, 16, v83
	buffer_load_dwordx2 v[158:159], v213, s[84:87], s98 offen nt
	v_cndmask_b32_e32 v21, 0, v21, vcc
	v_mul_f32_e32 v21, v21, v18
	ds_write_b16 v189, v22 offset:1360
	v_cvt_pk_bf16_f32 v22, v21, s0
	v_mul_f32_e32 v21, v21, v16
	v_cvt_pk_bf16_f32 v21, v21, s0
	ds_write_b16 v190, v21 offset:1632
	v_and_b32_e32 v21, 0xffff0000, v83
	v_cndmask_b32_e32 v21, 0, v21, vcc
	v_mul_f32_e32 v18, v21, v18
	v_mul_f32_e32 v16, v18, v16
	v_cvt_pk_bf16_f32 v16, v16, s0
	ds_write_b16 v190, v16 offset:1904
	v_sub_f32_e32 v16, v20, v17
	v_mul_f32_e32 v16, 0x3fb8aa3b, v16
	v_exp_f32_e32 v16, v16
	v_lshlrev_b32_e32 v17, 16, v84
	v_cmp_gt_u32_e32 vcc, s19, v169
	v_cvt_pk_bf16_f32 v21, v18, s0
	ds_write_b16 v189, v22 offset:1632
	v_cndmask_b32_e32 v17, 0, v17, vcc
	v_mul_f32_e32 v17, v17, v19
	v_cvt_pk_bf16_f32 v18, v17, s0
	v_mul_f32_e32 v17, v17, v16
	buffer_load_dwordx2 v[154:155], v213, s[84:87], s99 offen nt
	v_cvt_pk_bf16_f32 v17, v17, s0
	ds_write_b16 v192, v17
	v_and_b32_e32 v17, 0xffff0000, v84
	v_cndmask_b32_e32 v17, 0, v17, vcc
	v_mul_f32_e32 v17, v17, v19
	ds_write_b16 v189, v21 offset:1904
	ds_write_b16 v191, v18
	v_cvt_pk_bf16_f32 v18, v17, s0
	v_mul_f32_e32 v17, v17, v16
	v_cvt_pk_bf16_f32 v17, v17, s0
	ds_write_b16 v192, v17 offset:272
	v_lshlrev_b32_e32 v17, 16, v85
	v_cndmask_b32_e32 v17, 0, v17, vcc
	v_mul_f32_e32 v17, v17, v19
	ds_write_b16 v191, v18 offset:272
	v_cvt_pk_bf16_f32 v18, v17, s0
	v_mul_f32_e32 v17, v17, v16
	v_cvt_pk_bf16_f32 v17, v17, s0
	ds_write_b16 v192, v17 offset:544
	v_and_b32_e32 v17, 0xffff0000, v85
	v_cndmask_b32_e32 v17, 0, v17, vcc
	v_mul_f32_e32 v17, v17, v19
	ds_write_b16 v191, v18 offset:544
	v_cvt_pk_bf16_f32 v18, v17, s0
	buffer_load_dwordx2 v[148:149], v213, s[84:87], s100 offen nt
	v_mul_f32_e32 v17, v17, v16
	v_cvt_pk_bf16_f32 v17, v17, s0
	ds_write_b16 v192, v17 offset:816
	v_lshlrev_b32_e32 v17, 16, v86
	v_cndmask_b32_e32 v17, 0, v17, vcc
	v_mul_f32_e32 v17, v17, v19
	ds_write_b16 v191, v18 offset:816
	v_cvt_pk_bf16_f32 v18, v17, s0
	v_mul_f32_e32 v17, v17, v16
	v_cvt_pk_bf16_f32 v17, v17, s0
	ds_write_b16 v192, v17 offset:1088
	v_and_b32_e32 v17, 0xffff0000, v86
	v_cndmask_b32_e32 v17, 0, v17, vcc
	v_mul_f32_e32 v17, v17, v19
	ds_write_b16 v191, v18 offset:1088
	v_cvt_pk_bf16_f32 v18, v17, s0
	v_mul_f32_e32 v17, v17, v16
	v_cvt_pk_bf16_f32 v17, v17, s0
	ds_write_b16 v192, v17 offset:1360
	v_lshlrev_b32_e32 v17, 16, v87
	v_cndmask_b32_e32 v17, 0, v17, vcc
	v_mul_f32_e32 v17, v17, v19
	ds_write_b16 v191, v18 offset:1360
	v_cvt_pk_bf16_f32 v18, v17, s0
	buffer_load_dwordx2 v[146:147], v213, s[84:87], s101 offen nt
	v_mul_f32_e32 v17, v17, v16
	v_cvt_pk_bf16_f32 v17, v17, s0
	ds_write_b16 v192, v17 offset:1632
	v_and_b32_e32 v17, 0xffff0000, v87
	v_cndmask_b32_e32 v17, 0, v17, vcc
	v_mul_f32_e32 v17, v17, v19
	v_mul_f32_e32 v16, v17, v16
	ds_write_b16 v191, v18 offset:1632
	v_cvt_pk_bf16_f32 v18, v17, s0
	v_cvt_pk_bf16_f32 v16, v16, s0
	ds_write_b16 v191, v18 offset:1904
	ds_write_b16 v192, v16 offset:1904
	s_waitcnt lgkmcnt(0)
	s_barrier
	s_add_i32 s18, s17, 1
	s_cmp_eq_u32 s17, 32
	s_cselect_b64 s[6:7], -1, 0
	s_and_b64 vcc, exec, s[6:7]
	s_cbranch_vccnz .LBB0_321
